# P4 retention post-processing loop software-pipelined (next unit's loads issued one unit ahead); SS_SPLIT 0x400 (prompt scan is now the longer half of P3)
# speedup vs baseline: 1.0433x; 1.0016x over previous
.LBB0_740:
	v_readlane_b32 s90, v244, 3
	v_readlane_b32 s62, v244, 0
	v_readlane_b32 s58, v245, 58
	v_readlane_b32 s56, v245, 60
	s_bitcmp0_b32 s82, 4
	v_readlane_b32 s88, v244, 7
	v_readlane_b32 s91, v244, 4
	v_readlane_b32 s61, v244, 2
	v_readlane_b32 s63, v244, 1
	v_readlane_b32 s59, v245, 59
	v_readlane_b32 s57, v245, 61
	v_readlane_b32 s60, v244, 8
	s_cbranch_scc1 .LBB0_762
	s_lshl_b32 s0, s92, 3
	s_add_i32 s10, s84, s0
	s_addk_i32 s10, 0x400
	s_cmpk_gt_i32 s10, 0x7fff
	s_cbranch_scc1 .LBB0_762
	s_add_u32 s0, s96, 0xe800000
	s_addc_u32 s1, s97, 0
	s_add_u32 s8, s96, 0x10a40000
	s_addc_u32 s9, s97, 0
	v_readlane_b32 s12, v245, 6
	s_add_u32 s2, s96, 0x2f00000
	v_readlane_b32 s20, v245, 14
	s_addc_u32 s3, s97, 0
	v_readlane_b32 s13, v245, 7
	v_readlane_b32 s14, v245, 8
	v_readlane_b32 s15, v245, 9
	v_readlane_b32 s21, v245, 15
	s_add_u32 s20, s96, 0x17100000
	v_and_b32_e32 v2, 15, v208
	v_readlane_b32 s23, v245, 17
	s_addc_u32 s21, s97, 0
	v_readlane_b32 s12, v245, 0
	s_lshl_b32 s11, s60, 3
	v_mov_b32_e32 v1, 0
	v_lshlrev_b32_e32 v0, 4, v2
	v_readlane_b32 s18, v245, 12
	v_readlane_b32 s19, v245, 13
	v_readlane_b32 s13, v245, 1
	v_readlane_b32 s14, v245, 2
	v_readlane_b32 s15, v245, 3
	s_sub_i32 s23, 0, s11
	s_lshl_b32 s11, s88, 3
	v_readlane_b32 s24, v245, 18
	s_waitcnt vmcnt(0)
	v_lshl_add_u64 v[18:19], s[18:19], 0, v[0:1]
	v_lshl_add_u64 v[0:1], s[14:15], 0, v[0:1]
	s_mov_b64 s[12:13], 0x4ab1200
	s_add_i32 s11, s84, s11
	v_readlane_b32 s25, v245, 19
	v_readlane_b32 s26, v245, 20
	v_lshl_add_u64 v[20:21], v[0:1], 0, s[12:13]
	s_add_i32 s24, s11, 0x400
	s_lshl_b32 s11, s33, 3
	s_lshl_b32 s12, s60, 4
	v_readlane_b32 s22, v245, 16
	v_readlane_b32 s27, v245, 21
	s_sub_i32 s25, s11, s12
	s_lshl_b32 s26, s10, 2
	s_lshl_b32 s10, s33, 6
	s_lshl_b32 s11, s60, 6
	v_lshrrev_b32_e32 v17, 4, v179
	v_lshlrev_b32_e32 v16, 2, v2
	v_cmp_ne_u32_e64 s[4:5], 0, v2
	v_cmp_eq_u32_e64 s[6:7], 0, v2
	s_lshl_b32 s22, s76, 4
	s_sub_i32 s27, s10, s11
	v_readlane_b32 s16, v245, 10
	v_readlane_b32 s17, v245, 11
	s_branch .LBB0_744

.LBB0_798:
	s_bitcmp0_b32 s82, 4
	s_cbranch_scc1 .LBB0_820
	s_lshl_b32 s0, s88, 3
	s_add_i32 s2, s84, s0
	s_cmp_gt_i32 s2, 0x3ff
	s_cbranch_scc1 .LBB0_820
	v_readlane_b32 s4, v245, 6
	s_lshl_b32 s3, s60, 3
	v_readlane_b32 s6, v245, 8
	v_readlane_b32 s7, v245, 9
	s_add_u32 s6, s96, 0xe800000
	v_readlane_b32 s8, v245, 10
	s_addc_u32 s7, s97, 0
	v_readlane_b32 s9, v245, 11
	s_add_u32 s8, s96, 0x10a40000
	v_readlane_b32 s12, v245, 14
	v_readlane_b32 s13, v245, 15
	v_readlane_b32 s14, v245, 16
	v_readlane_b32 s15, v245, 17
	s_addc_u32 s9, s97, 0
	s_add_u32 s20, s96, 0x2f00000
	v_readlane_b32 s12, v245, 0
	s_waitcnt vmcnt(5)
	v_mov_b32_e32 v1, 0
	v_lshlrev_b32_e32 v0, 4, v70
	v_readlane_b32 s10, v245, 12
	v_readlane_b32 s11, v245, 13
	s_addc_u32 s21, s97, 0
	v_readlane_b32 s14, v245, 2
	v_readlane_b32 s15, v245, 3
	v_lshl_add_u64 v[18:19], s[10:11], 0, v[0:1]
	s_add_u32 s22, s96, 0x17100000
	v_lshl_add_u64 v[0:1], s[14:15], 0, v[0:1]
	s_mov_b64 s[10:11], 0x4ab1200
	v_readlane_b32 s5, v245, 7
	s_addc_u32 s23, s97, 0
	s_waitcnt vmcnt(4)
	v_lshl_add_u64 v[20:21], v[0:1], 0, s[10:11]
	s_lshl_b32 s10, s88, 5
	s_lshl_b32 s11, s84, 2
	v_lshlrev_b32_e32 v16, 2, v70
	v_cmp_ne_u32_e64 s[0:1], 0, v70
	v_cmp_eq_u32_e64 s[4:5], 0, v70
	s_lshl_b32 s24, s60, 4
	s_add_i32 s25, s10, s11
	s_lshl_b32 s26, s60, 6
	v_readlane_b32 s16, v245, 18
	v_readlane_b32 s17, v245, 19
	v_readlane_b32 s18, v245, 20
	v_readlane_b32 s19, v245, 21
	v_readlane_b32 s13, v245, 1
	s_branch .LBB0_802
.LBB0_801:
	s_add_i32 s2, s2, s24
	s_add_i32 s25, s25, s26
	s_cmp_gt_i32 s2, 0x3ff
	s_cbranch_scc1 .LBB0_820
.LBB0_802:
	s_ashr_i32 s29, s2, 8
	s_lshl_b32 s10, s29, 10
	s_and_b32 s28, s25, 0x3c0
	v_readlane_b32 s36, v245, 6
	s_or_b32 s34, s28, s10
	s_mul_i32 s11, s29, 0x3480
	v_readlane_b32 s40, v245, 10
	s_mul_hi_i32 s10, s29, 0x3480
	v_readlane_b32 s41, v245, 11
	s_add_u32 s14, s40, s11
	s_addc_u32 s15, s41, s10
	s_add_i32 s18, s3, s2
	s_cmp_lt_i32 s18, 0x400
	s_cselect_b64 s[10:11], -1, 0
	s_cmp_gt_i32 s18, 0x3ff
	s_cselect_b64 s[12:13], -1, 0
	s_and_b64 s[16:17], s[12:13], exec
	s_cselect_b32 s16, s2, s18
	s_ashr_i32 s35, s16, 8
	s_lshl_b32 s36, s16, 2
	v_readlane_b32 s37, v245, 7
	s_lshl_b32 s16, s35, 10
	s_and_b32 s27, s36, 0x3c0
	s_or_b32 s37, s27, s16
	s_mul_i32 s17, s35, 0x3480
	s_mul_hi_i32 s16, s35, 0x3480
	s_add_u32 s18, s40, s17
	s_addc_u32 s19, s41, s16
	s_lshl_b32 s29, s29, 2
	s_add_i32 s16, s29, 0x2040
	s_ashr_i32 s17, s16, 31
	s_lshl_b64 s[30:31], s[16:17], 10
	s_or_b32 s30, s30, s28
	v_mov_b32_e32 v5, s31
	v_or_b32_e32 v4, s30, v16
	v_lshl_add_u64 v[0:1], v[4:5], 3, s[8:9]
	v_and_or_b32 v29, s25, 60, v61
	global_load_dwordx4 v[38:41], v[0:1], off
	global_load_dwordx4 v[42:45], v[0:1], off offset:16
	v_or_b32_e32 v0, s34, v29
	v_ashrrev_i32_e32 v1, 31, v0
	v_readlane_b32 s42, v245, 12
	v_readlane_b32 s43, v245, 13
	v_readlane_b32 s44, v245, 14
	v_readlane_b32 s45, v245, 15
	v_readlane_b32 s46, v245, 16
	v_readlane_b32 s47, v245, 17
	v_readlane_b32 s48, v245, 18
	v_readlane_b32 s49, v245, 19
	v_readlane_b32 s50, v245, 20
	v_readlane_b32 s51, v245, 21
	v_lshlrev_b64 v[22:23], 8, v[0:1]
	v_or_b32_e32 v0, s28, v29
	v_or_b32_e32 v0, 0x800, v0
	s_mul_i32 s30, s16, 0x3480
	v_readlane_b32 s40, v245, 22
	v_lshlrev_b32_e32 v27, 2, v0
	s_mul_hi_i32 s31, s16, 0x3480
	s_add_u32 s30, s20, s30
	v_readlane_b32 s41, v245, 23
	s_addc_u32 s31, s21, s31
	s_nop 3
	global_load_dword v26, v27, s[40:41]
	global_load_dword v33, v27, s[14:15]
	global_load_dword v32, v27, s[30:31]
	s_lshl_b32 s30, s35, 2
	s_add_i32 s14, s30, 0x2040
	v_lshl_add_u64 v[0:1], v[18:19], 0, v[22:23]
	v_and_or_b32 v30, s36, 60, v61
	s_ashr_i32 s15, s14, 31
	global_load_dwordx4 v[46:49], v[0:1], off
	v_or_b32_e32 v0, s37, v30
	s_lshl_b64 s[34:35], s[14:15], 10
	v_ashrrev_i32_e32 v1, 31, v0
	v_or_b32_e32 v6, s27, v30
	v_lshl_add_u64 v[4:5], v[4:5], 2, s[6:7]
	s_or_b32 s31, s34, s27
	v_lshlrev_b64 v[24:25], 8, v[0:1]
	v_or_b32_e32 v6, 0x800, v6
	global_load_dwordx4 v[50:53], v[4:5], off
	v_mov_b32_e32 v5, s35
	v_or_b32_e32 v4, s31, v16
	s_mul_i32 s34, s14, 0x3480
	v_lshl_add_u64 v[0:1], v[18:19], 0, v[24:25]
	v_lshlrev_b32_e32 v28, 2, v6
	v_lshl_add_u64 v[6:7], v[4:5], 2, s[6:7]
	v_lshl_add_u64 v[12:13], v[4:5], 3, s[8:9]
	s_mul_hi_i32 s31, s14, 0x3480
	s_add_u32 s34, s20, s34
	global_load_dwordx4 v[0:3], v[0:1], off
	s_nop 0
	global_load_dwordx4 v[8:11], v[12:13], off offset:16
	s_nop 0
	global_load_dwordx4 v[4:7], v[6:7], off
	s_nop 0
	global_load_dwordx4 v[12:15], v[12:13], off
	s_addc_u32 s35, s21, s31
	global_load_dword v17, v28, s[40:41]
	global_load_dword v37, v28, s[18:19]
	global_load_dword v31, v28, s[34:35]
	s_add_i32 s64, s29, 0x2041
	s_ashr_i32 s65, s64, 31
	s_lshl_b64 s[66:67], s[64:65], 10
	v_mov_b32_e32 v236, s28
	v_or3_b32 v236, s66, v236, v16
	v_or3_b32 v237, s67, 0, 0
	s_mul_hi_i32 s67, s64, 0x3480
	s_mul_i32 s66, s64, 0x3480
	s_add_u32 s66, s20, s66
	s_addc_u32 s67, s21, s67
	v_lshl_add_u64 v[238:239], v[236:237], 3, s[8:9]
	global_load_dwordx4 v[148:151], v[238:239], off
	global_load_dwordx4 v[152:155], v[238:239], off offset:16
	global_load_dword v172, v27, s[66:67]
	v_lshl_add_u64 v[238:239], v[236:237], 2, s[6:7]
	global_load_dwordx4 v[156:159], v[238:239], off
	s_add_i32 s64, s30, 0x2041
	s_ashr_i32 s65, s64, 31
	s_lshl_b64 s[66:67], s[64:65], 10
	v_mov_b32_e32 v236, s27
	v_or3_b32 v236, s66, v236, v16
	v_or3_b32 v237, s67, 0, 0
	s_mul_hi_i32 s67, s64, 0x3480
	s_mul_i32 s66, s64, 0x3480
	s_add_u32 s66, s20, s66
	s_addc_u32 s67, s21, s67
	v_lshl_add_u64 v[238:239], v[236:237], 3, s[8:9]
	global_load_dwordx4 v[160:163], v[238:239], off
	global_load_dwordx4 v[164:167], v[238:239], off offset:16
	global_load_dword v173, v28, s[66:67]
	v_lshl_add_u64 v[238:239], v[236:237], 2, s[6:7]
	global_load_dwordx4 v[168:171], v[238:239], off
	s_add_i32 s64, s29, 0x2042
	s_ashr_i32 s65, s64, 31
	s_lshl_b64 s[66:67], s[64:65], 10
	v_mov_b32_e32 v236, s28
	v_or3_b32 v236, s66, v236, v16
	v_or3_b32 v237, s67, 0, 0
	s_mul_hi_i32 s67, s64, 0x3480
	s_mul_i32 s66, s64, 0x3480
	s_add_u32 s66, s20, s66
	s_addc_u32 s67, s21, s67
	v_lshl_add_u64 v[238:239], v[236:237], 3, s[8:9]
	global_load_dwordx4 v[180:183], v[238:239], off
	global_load_dwordx4 v[184:187], v[238:239], off offset:16
	global_load_dword v204, v27, s[66:67]
	v_lshl_add_u64 v[238:239], v[236:237], 2, s[6:7]
	global_load_dwordx4 v[188:191], v[238:239], off
	s_add_i32 s64, s30, 0x2042
	s_ashr_i32 s65, s64, 31
	s_lshl_b64 s[66:67], s[64:65], 10
	v_mov_b32_e32 v236, s27
	v_or3_b32 v236, s66, v236, v16
	v_or3_b32 v237, s67, 0, 0
	s_mul_hi_i32 s67, s64, 0x3480
	s_mul_i32 s66, s64, 0x3480
	s_add_u32 s66, s20, s66
	s_addc_u32 s67, s21, s67
	v_lshl_add_u64 v[238:239], v[236:237], 3, s[8:9]
	global_load_dwordx4 v[192:195], v[238:239], off
	global_load_dwordx4 v[196:199], v[238:239], off offset:16
	global_load_dword v205, v28, s[66:67]
	v_lshl_add_u64 v[238:239], v[236:237], 2, s[6:7]
	global_load_dwordx4 v[200:203], v[238:239], off
	s_add_i32 s64, s29, 0x2043
	s_ashr_i32 s65, s64, 31
	s_lshl_b64 s[66:67], s[64:65], 10
	v_mov_b32_e32 v236, s28
	v_or3_b32 v236, s66, v236, v16
	v_or3_b32 v237, s67, 0, 0
	s_mul_hi_i32 s67, s64, 0x3480
	s_mul_i32 s66, s64, 0x3480
	s_add_u32 s66, s20, s66
	s_addc_u32 s67, s21, s67
	v_lshl_add_u64 v[238:239], v[236:237], 3, s[8:9]
	global_load_dwordx4 v[210:213], v[238:239], off
	global_load_dwordx4 v[214:217], v[238:239], off offset:16
	global_load_dword v234, v27, s[66:67]
	v_lshl_add_u64 v[238:239], v[236:237], 2, s[6:7]
	global_load_dwordx4 v[218:221], v[238:239], off
	s_add_i32 s64, s30, 0x2043
	s_ashr_i32 s65, s64, 31
	s_lshl_b64 s[66:67], s[64:65], 10
	v_mov_b32_e32 v236, s27
	v_or3_b32 v236, s66, v236, v16
	v_or3_b32 v237, s67, 0, 0
	s_mul_hi_i32 s67, s64, 0x3480
	s_mul_i32 s66, s64, 0x3480
	s_add_u32 s66, s20, s66
	s_addc_u32 s67, s21, s67
	v_lshl_add_u64 v[238:239], v[236:237], 3, s[8:9]
	global_load_dwordx4 v[222:225], v[238:239], off
	global_load_dwordx4 v[226:229], v[238:239], off offset:16
	global_load_dword v235, v28, s[66:67]
	v_lshl_add_u64 v[238:239], v[236:237], 2, s[6:7]
	global_load_dwordx4 v[230:233], v[238:239], off
	v_lshlrev_b32_e32 v29, 2, v29
	v_readlane_b32 s38, v245, 8
	v_readlane_b32 s39, v245, 9
	v_readlane_b32 s42, v245, 24
	v_readlane_b32 s43, v245, 25
	v_readlane_b32 s44, v245, 26
	v_readlane_b32 s45, v245, 27
	v_readlane_b32 s46, v245, 28
	v_readlane_b32 s47, v245, 29
	v_readlane_b32 s48, v245, 30
	v_readlane_b32 s49, v245, 31
	v_readlane_b32 s50, v245, 32
	v_readlane_b32 s51, v245, 33
	v_readlane_b32 s52, v245, 34
	v_readlane_b32 s53, v245, 35
	v_readlane_b32 s54, v245, 36
	v_readlane_b32 s55, v245, 37
	s_waitcnt vmcnt(37)
	v_lshlrev_b32_e32 v55, 16, v40
	v_and_b32_e32 v35, 0xffff0000, v40
	v_lshlrev_b32_e32 v40, 16, v39
	v_lshlrev_b32_e32 v54, 16, v38
	s_waitcnt vmcnt(36)
	v_lshlrev_b32_e32 v56, 16, v42
	v_lshlrev_b32_e32 v57, 16, v44
	v_and_b32_e32 v34, 0xffff0000, v38
	v_and_b32_e32 v36, 0xffff0000, v42
	v_and_b32_e32 v38, 0xffff0000, v44
	v_lshlrev_b32_e32 v42, 16, v41
	v_lshlrev_b32_e32 v44, 16, v43
	v_lshlrev_b32_e32 v58, 16, v45
	v_and_b32_e32 v39, 0xffff0000, v39
	v_and_b32_e32 v41, 0xffff0000, v41
	v_and_b32_e32 v43, 0xffff0000, v43
	v_and_b32_e32 v45, 0xffff0000, v45
	s_waitcnt vmcnt(33)
	v_sub_f32_e32 v33, v33, v32
	v_fma_f32 v59, v26, v33, v32
	s_waitcnt vmcnt(32)
	v_mul_f32 v33, v46, v40
	v_mul_f32 v40, v48, v44
	v_mul_f32 v34, v59, v34
	v_mul_f32 v35, v59, v35
	s_nop 0
	v_fma_f32 v33, v47, v42, v33
	v_fma_f32 v40, v49, v58, v40
	s_nop 0
	v_add_f32 v33, v33, v40
	s_nop 1
	v_add_f32_dpp v33, v33, v33 row_ror:8 row_mask:0xf bank_mask:0xf bound_ctrl:1
	s_nop 1
	v_add_f32_dpp v33, v33, v33 row_ror:4 row_mask:0xf bank_mask:0xf bound_ctrl:1
	s_nop 1
	v_add_f32_dpp v33, v33, v33 row_ror:2 row_mask:0xf bank_mask:0xf bound_ctrl:1
	s_nop 1
	v_add_f32_dpp v40, v33, v33 row_ror:1 row_mask:0xf bank_mask:0xf bound_ctrl:1
	v_fma_f32 v33, v40, v39, v34
	v_fma_f32 v34, v40, v41, v35
	v_mul_f32 v35, v59, v36
	v_mul_f32 v36, v59, v38
	s_waitcnt vmcnt(31)
	v_fma_f32 v33, v46, v50, v33
	v_fma_f32 v35, v40, v43, v35
	v_fma_f32 v34, v47, v51, v34
	v_fma_f32 v36, v40, v45, v36
	s_nop 0
	v_mul_f32 v38, v33, v54
	v_fma_f32 v35, v48, v52, v35
	v_fma_f32 v36, v49, v53, v36
	s_nop 0
	v_fma_f32 v38, v34, v55, v38
	v_mul_f32 v39, v35, v56
	s_nop 0
	v_fma_f32 v39, v36, v57, v39
	s_nop 0
	v_add_f32 v38, v38, v39
	v_mov_b32_e32 v39, 0
	s_nop 0
	v_add_f32_dpp v38, v38, v38 row_ror:8 row_mask:0xf bank_mask:0xf bound_ctrl:1
	s_nop 1
	v_add_f32_dpp v38, v38, v38 row_ror:4 row_mask:0xf bank_mask:0xf bound_ctrl:1
	s_nop 1
	v_add_f32_dpp v38, v38, v38 row_ror:2 row_mask:0xf bank_mask:0xf bound_ctrl:1
	s_nop 1
	v_mov_b32_dpp v39, v38 row_ror:1 row_mask:0xf bank_mask:0xf
	s_and_saveexec_b64 s[18:19], s[4:5]
	s_cbranch_execz .LBB0_804
	s_lshl_b64 s[16:17], s[16:17], 12
	s_add_u32 s16, s22, s16
	s_addc_u32 s17, s23, s17
	s_lshl_b32 s31, s28, 2
	s_add_u32 s16, s16, s31
	s_addc_u32 s17, s17, 0
	v_add_f32_e32 v38, v38, v39
	global_store_dword v29, v38, s[16:17]

.LBB0_888:
	s_cmp_gt_i32 s2, 0x80ff
	s_cbranch_scc1 .LBB0_891
	s_waitcnt vmcnt(0)
	v_mbcnt_lo_u32_b32 v0, -1, 0
	v_mbcnt_hi_u32_b32 v0, -1, v0
	v_and_b32_e32 v1, 64, v0
	v_add_u32_e32 v1, 64, v1
	v_xor_b32_e32 v2, 1, v0
	v_cmp_lt_i32_e32 vcc, v2, v1
	s_add_u32 s3, s96, 0x19340000
	s_addc_u32 s14, s97, 0
	v_cndmask_b32_e32 v2, v0, v2, vcc
	v_lshlrev_b32_e32 v7, 2, v2
	v_xor_b32_e32 v2, 2, v0
	v_cmp_lt_i32_e32 vcc, v2, v1
	s_lshl_b32 s0, s88, 11
	s_lshl_b32 s1, s84, 8
	v_cndmask_b32_e32 v2, v0, v2, vcc
	v_lshlrev_b32_e32 v8, 2, v2
	v_xor_b32_e32 v2, 4, v0
	v_cmp_lt_i32_e32 vcc, v2, v1
	v_lshlrev_b32_e32 v6, 2, v179
	s_lshl_b32 s15, s33, 3
	v_cndmask_b32_e32 v2, v0, v2, vcc
	v_lshlrev_b32_e32 v9, 2, v2
	v_xor_b32_e32 v2, 8, v0
	v_cmp_lt_i32_e32 vcc, v2, v1
	s_add_i32 s16, s0, s1
	s_lshl_b32 s17, s33, 11
	v_cndmask_b32_e32 v2, v0, v2, vcc
	v_lshlrev_b32_e32 v10, 2, v2
	v_xor_b32_e32 v2, 16, v0
	v_cmp_lt_i32_e32 vcc, v2, v1
	v_mov_b32_e32 v13, 0x358637bd
	s_mov_b32 s18, 0xf800000
	v_cndmask_b32_e32 v2, v0, v2, vcc
	v_lshlrev_b32_e32 v11, 2, v2
	v_xor_b32_e32 v2, 32, v0
	v_cmp_lt_i32_e32 vcc, v2, v1
	v_mov_b32_e32 v14, 0x260
	v_mov_b32_e32 v5, 0
	v_cndmask_b32_e32 v0, v0, v2, vcc
	v_lshlrev_b32_e32 v12, 2, v0
	s_mov_b32 s19, 0xa201000
	s_mov_b32 s20, 0xbfb8aa3b
	s_mov_b32 s21, 0x42ce8ed0
	s_mov_b32 s22, 0xc2b17218
	v_mov_b32_e32 v15, 0x7f800000
	s_movk_i32 s23, 0x7fff
	v_mov_b32_e32 v16, 1
	v_mov_b32_e32 v61, 0
	s_ashr_i32 s4, s2, 2
	s_and_b32 s0, s16, 0x300
	s_ashr_i32 s5, s4, 31
	v_or_b32_e32 v57, s0, v6
	s_lshl_b64 s[0:1], s[4:5], 12
	s_add_u32 s6, s3, s0
	v_lshlrev_b32_e32 v58, 2, v57
	s_addc_u32 s7, s14, s1
	s_lshl_b64 s[4:5], s[4:5], 13
	v_lshlrev_b32_e32 v60, 1, v57
	global_load_dwordx4 v[48:51], v58, s[6:7]
	s_add_u32 s4, s96, s4
	s_addc_u32 s5, s97, s5
	v_lshl_add_u64 v[62:63], s[4:5], 0, v[60:61]
	v_add_co_u32_e32 v62, vcc, s19, v62
	s_sub_u32 s0, 0, s0
	s_nop 0
	v_addc_co_u32_e32 v63, vcc, 0, v63, vcc
	global_load_dwordx2 v[52:53], v[62:63], off offset:2048
	s_subb_u32 s1, 0, s1
	s_add_u32 s0, s4, s0
	s_addc_u32 s1, s5, s1
	v_lshl_add_u64 v[54:55], s[0:1], 0, v[60:61]
	global_load_dword v56, v58, s[6:7]
.LBB0_890:
	s_waitcnt vmcnt(1)
	v_mov_b32_e32 v0, v48
	v_mov_b32_e32 v1, v49
	v_mov_b32_e32 v2, v50
	v_mov_b32_e32 v3, v51
	v_mov_b32_e32 v18, v52
	v_mov_b32_e32 v19, v53
	v_mov_b32_e32 v20, v54
	v_mov_b32_e32 v21, v55
	s_add_i32 s2, s2, s15
	s_add_i32 s16, s16, s17
	s_ashr_i32 s4, s2, 2
	s_and_b32 s0, s16, 0x300
	s_ashr_i32 s5, s4, 31
	v_or_b32_e32 v57, s0, v6
	s_lshl_b64 s[0:1], s[4:5], 12
	s_add_u32 s6, s3, s0
	v_lshlrev_b32_e32 v58, 2, v57
	s_addc_u32 s7, s14, s1
	s_lshl_b64 s[4:5], s[4:5], 13
	v_lshlrev_b32_e32 v60, 1, v57
	global_load_dwordx4 v[48:51], v58, s[6:7]
	s_add_u32 s4, s96, s4
	s_addc_u32 s5, s97, s5
	v_lshl_add_u64 v[62:63], s[4:5], 0, v[60:61]
	v_add_co_u32_e32 v62, vcc, s19, v62
	s_sub_u32 s0, 0, s0
	s_nop 0
	v_addc_co_u32_e32 v63, vcc, 0, v63, vcc
	global_load_dwordx2 v[52:53], v[62:63], off offset:2048
	s_subb_u32 s1, 0, s1
	s_add_u32 s0, s4, s0
	s_addc_u32 s1, s5, s1
	v_lshl_add_u64 v[54:55], s[0:1], 0, v[60:61]
	s_cmp_gt_i32 s2, 0x80ff
	v_pk_mul_f32 v[22:23], v[2:3], v[2:3]
	v_pk_mul_f32 v[24:25], v[0:1], v[0:1]
	v_mov_b32_e32 v26, v0
	v_mov_b32_e32 v27, v2
	v_mov_b32_e32 v2, v1
	v_pk_mov_b32 v[0:1], v[24:25], v[22:23] op_sel:[1,0]
	v_mov_b32_e32 v25, v23
	v_pk_add_f32 v[0:1], v[0:1], v[24:25]
	v_lshlrev_b32_e32 v17, 16, v19
	v_add_f32_e32 v0, v0, v1
	ds_bpermute_b32 v1, v7, v0
	v_lshlrev_b32_e32 v24, 16, v18
	v_and_b32_e32 v25, 0xffff0000, v19
	v_and_b32_e32 v28, 0xffff0000, v18
	v_mul_f32_e32 v4, 0xbfb8aa3b, v24
	v_mul_f32_e32 v18, 0xbfb8aa3b, v28
	v_mul_f32_e32 v19, 0xbfb8aa3b, v17
	v_mul_f32_e32 v22, 0xbfb8aa3b, v25
	v_fma_f32 v23, v24, s20, -v4
	v_rndne_f32_e32 v29, v4
	v_fma_f32 v30, v28, s20, -v18
	v_rndne_f32_e32 v31, v18
	v_fma_f32 v32, v17, s20, -v19
	v_rndne_f32_e32 v33, v19
	v_fma_f32 v34, v25, s20, -v22
	v_rndne_f32_e32 v35, v22
	v_fmac_f32_e32 v23, 0xb2a5705f, v24
	v_sub_f32_e32 v4, v4, v29
	v_fmac_f32_e32 v30, 0xb2a5705f, v28
	v_sub_f32_e32 v18, v18, v31
	v_fmac_f32_e32 v32, 0xb2a5705f, v17
	v_sub_f32_e32 v19, v19, v33
	v_fmac_f32_e32 v34, 0xb2a5705f, v25
	v_sub_f32_e32 v22, v22, v35
	v_add_f32_e32 v4, v4, v23
	v_add_f32_e32 v18, v18, v30
	v_add_f32_e32 v19, v19, v32
	v_add_f32_e32 v22, v22, v34
	s_waitcnt lgkmcnt(0)
	v_add_f32_e32 v0, v0, v1
	v_cvt_i32_f32_e32 v29, v29
	v_cvt_i32_f32_e32 v31, v31
	v_cvt_i32_f32_e32 v33, v33
	v_exp_f32_e32 v1, v4
	v_exp_f32_e32 v4, v18
	v_exp_f32_e32 v18, v19
	v_exp_f32_e32 v19, v22
	ds_bpermute_b32 v22, v8, v0
	v_ldexp_f32 v1, v1, v29
	v_ldexp_f32 v4, v4, v31
	v_cmp_nlt_f32_e32 vcc, s21, v28
	v_ldexp_f32 v18, v18, v33
	v_cmp_nlt_f32_e64 s[0:1], s21, v17
	v_cmp_nlt_f32_e64 s[6:7], s21, v24
	v_cndmask_b32_e32 v4, 0, v4, vcc
	v_cmp_ngt_f32_e32 vcc, s22, v28
	v_cndmask_b32_e64 v1, 0, v1, s[6:7]
	v_cmp_ngt_f32_e64 s[6:7], s22, v24
	v_cndmask_b32_e64 v23, 0, v18, s[0:1]
	v_cmp_ngt_f32_e64 s[0:1], s22, v17
	s_waitcnt lgkmcnt(0)
	v_add_f32_e32 v22, v0, v22
	v_cndmask_b32_e64 v0, v15, v1, s[6:7]
	v_cndmask_b32_e32 v18, v15, v4, vcc
	v_cndmask_b32_e64 v1, v15, v23, s[0:1]
	ds_bpermute_b32 v4, v9, v22
	v_pk_add_f32 v[0:1], v[0:1], 1.0 op_sel_hi:[1,0]
	v_cvt_i32_f32_e32 v35, v35
	v_div_scale_f32 v23, s[0:1], v1, v1, v17
	v_rcp_f32_e32 v36, v23
	s_waitcnt lgkmcnt(0)
	v_add_f32_e32 v4, v22, v4
	ds_bpermute_b32 v22, v10, v4
	v_div_scale_f32 v29, s[0:1], v17, v1, v17
	v_fma_f32 v40, -v23, v36, 1.0
	v_fmac_f32_e32 v36, v40, v36
	v_mul_f32_e32 v40, v29, v36
	v_fma_f32 v44, -v23, v40, v29
	v_fmac_f32_e32 v40, v44, v36
	s_waitcnt lgkmcnt(0)
	v_add_f32_e32 v4, v4, v22
	v_fma_f32 v22, -v23, v40, v29
	ds_bpermute_b32 v23, v11, v4
	v_ldexp_f32 v19, v19, v35
	v_cmp_nlt_f32_e64 s[4:5], s21, v25
	s_waitcnt lgkmcnt(0)
	v_add_f32_e32 v4, v4, v23
	v_cndmask_b32_e64 v19, 0, v19, s[4:5]
	v_cmp_ngt_f32_e64 s[4:5], s22, v25
	ds_bpermute_b32 v23, v12, v4
	s_waitcnt lgkmcnt(0)
	v_add_f32_e32 v4, v4, v23
	v_cndmask_b32_e64 v19, v15, v19, s[4:5]
	v_pk_add_f32 v[18:19], v[18:19], 1.0 op_sel_hi:[1,0]
	v_div_scale_f32 v30, s[4:5], v0, v0, v24
	v_div_scale_f32 v32, s[6:7], v19, v19, v25
	v_div_scale_f32 v34, s[8:9], v18, v18, v28
	v_rcp_f32_e32 v37, v30
	v_rcp_f32_e32 v38, v32
	v_rcp_f32_e32 v39, v34
	v_fmamk_f32 v4, v4, 0x3b800000, v13
	v_mul_f32_e32 v23, 0x4f800000, v4
	v_cmp_gt_f32_e32 vcc, s18, v4
	v_fma_f32 v41, -v30, v37, 1.0
	v_fma_f32 v42, -v32, v38, 1.0
	v_cndmask_b32_e32 v4, v4, v23, vcc
	v_div_scale_f32 v31, s[4:5], v24, v0, v24
	v_div_scale_f32 v33, s[6:7], v25, v19, v25
	v_fma_f32 v43, -v34, v39, 1.0
	v_fmac_f32_e32 v37, v41, v37
	v_fmac_f32_e32 v38, v42, v38
	v_sqrt_f32_e32 v23, v4
	v_div_scale_f32 v35, s[8:9], v28, v18, v28
	v_fmac_f32_e32 v39, v43, v39
	v_mul_f32_e32 v41, v31, v37
	v_mul_f32_e32 v42, v33, v38
	v_mul_f32_e32 v43, v35, v39
	v_fma_f32 v45, -v30, v41, v31
	v_fma_f32 v46, -v32, v42, v33
	v_fma_f32 v47, -v34, v43, v35
	v_fmac_f32_e32 v41, v45, v37
	v_fmac_f32_e32 v42, v46, v38
	v_fmac_f32_e32 v43, v47, v39
	v_fma_f32 v29, -v30, v41, v31
	v_fma_f32 v30, -v32, v42, v33
	v_add_u32_e32 v32, -1, v23
	v_fma_f32 v31, -v34, v43, v35
	v_add_u32_e32 v33, 1, v23
	v_fma_f32 v34, -v32, v23, v4
	v_fma_f32 v35, -v33, v23, v4
	v_cmp_ge_f32_e64 s[10:11], 0, v34
	s_nop 1
	v_cndmask_b32_e64 v23, v23, v32, s[10:11]
	v_cmp_lt_f32_e64 s[10:11], 0, v35
	s_nop 1
	v_cndmask_b32_e64 v23, v23, v33, s[10:11]
	v_mul_f32_e32 v32, 0x37800000, v23
	v_cndmask_b32_e32 v23, v23, v32, vcc
	v_cmp_class_f32_e32 vcc, v4, v14
	s_nop 1
	v_cndmask_b32_e32 v4, v23, v4, vcc
	v_div_scale_f32 v23, s[10:11], v4, v4, 1.0
	v_rcp_f32_e32 v33, v23
	v_div_scale_f32 v32, vcc, 1.0, v4, 1.0
	v_fma_f32 v34, -v23, v33, 1.0
	v_fmac_f32_e32 v33, v34, v33
	v_mul_f32_e32 v34, v32, v33
	v_fma_f32 v35, -v23, v34, v32
	v_fmac_f32_e32 v34, v35, v33
	v_fma_f32 v23, -v23, v34, v32
	v_div_fmas_f32 v23, v23, v33, v34
	s_mov_b64 vcc, s[0:1]
	v_div_fmas_f32 v32, v22, v36, v40
	s_mov_b64 vcc, s[4:5]
	v_div_fixup_f32 v4, v23, v4, 1.0
	v_div_fixup_f32 v1, v32, v1, v17
	v_div_fmas_f32 v17, v29, v37, v41
	s_mov_b64 vcc, s[6:7]
	v_pk_mul_f32 v[22:23], v[26:27], v[4:5] op_sel_hi:[1,0]
	v_pk_mul_f32 v[2:3], v[2:3], v[4:5] op_sel_hi:[1,0]
	v_div_fmas_f32 v4, v30, v38, v42
	s_mov_b64 vcc, s[8:9]
	v_div_fixup_f32 v0, v17, v0, v24
	v_div_fixup_f32 v19, v4, v19, v25
	v_div_fmas_f32 v4, v31, v39, v43
	v_pk_mul_f32 v[0:1], v[22:23], v[0:1]
	v_div_fixup_f32 v18, v4, v18, v28
	v_and_b32_sdwa v4, v1, v16 dst_sel:DWORD dst_unused:UNUSED_PAD src0_sel:WORD_1 src1_sel:DWORD
	v_and_b32_sdwa v17, v0, v16 dst_sel:DWORD dst_unused:UNUSED_PAD src0_sel:WORD_1 src1_sel:DWORD
	v_pk_mul_f32 v[2:3], v[2:3], v[18:19]
	v_add3_u32 v0, v0, v17, s23
	v_add3_u32 v1, v1, v4, s23
	v_and_b32_sdwa v4, v3, v16 dst_sel:DWORD dst_unused:UNUSED_PAD src0_sel:WORD_1 src1_sel:DWORD
	v_and_b32_sdwa v17, v2, v16 dst_sel:DWORD dst_unused:UNUSED_PAD src0_sel:WORD_1 src1_sel:DWORD
	v_add3_u32 v3, v3, v4, s23
	v_add3_u32 v2, v2, v17, s23
	v_add_co_u32_e32 v20, vcc, 0xc00000, v20
	v_and_b32_e32 v3, 0xffff0000, v3
	v_and_b32_e32 v2, 0xffff0000, v2
	v_addc_co_u32_e32 v21, vcc, 0, v21, vcc
	v_or_b32_sdwa v1, v3, v1 dst_sel:DWORD dst_unused:UNUSED_PAD src0_sel:DWORD src1_sel:WORD_1
	v_or_b32_sdwa v0, v2, v0 dst_sel:DWORD dst_unused:UNUSED_PAD src0_sel:DWORD src1_sel:WORD_1
	global_store_dwordx2 v[20:21], v[0:1], off offset:2048
	s_cbranch_scc0 .LBB0_890
